# v021: sample-sequence SGU block: LayerNorm reduce reads batched (8 ds_read per wait instead of 1), tril W_s rows and b_s loads hoisted to block top
# baseline (speedup 1.0000x reference)
.LBB0_103:
	s_or_b64 exec, exec, s[0:1]
	s_mov_b64 s[0:1], s[40:41]
	s_waitcnt lgkmcnt(0)
	s_barrier
	s_lshl_b64 s[4:5], s[16:17], 14
	s_add_u32 s0, s0, s4
	s_addc_u32 s1, s1, s5
	v_lshl_add_u64 v[2:3], v[64:65], 2, s[0:1]
	s_mov_b64 s[0:1], 0x7cf8000
	v_lshl_add_u64 v[18:19], v[2:3], 0, s[0:1]
	v_readlane_b32 s0, v251, 9
	s_mov_b32 s4, 0x3b000000
	s_ashr_i32 s3, s2, 31
	s_lshl_b64 s[20:21], s[2:3], 7
	v_readlane_b32 s22, v253, 61
	v_readlane_b32 s23, v253, 62
	s_add_u32 s20, s20, s22
	s_addc_u32 s21, s21, s23
	s_lshl_b64 s[20:21], s[20:21], 9
	v_readlane_b32 s22, v250, 19
	v_readlane_b32 s23, v250, 20
	s_add_u32 s20, s22, s20
	s_addc_u32 s21, s23, s21
	s_lshl_b64 s[22:23], s[2:3], 9
	v_readlane_b32 s24, v253, 51
	v_readlane_b32 s25, v253, 52
	s_add_u32 s22, s24, s22
	s_addc_u32 s23, s25, s23
	global_load_dwordx4 v[142:145], v193, s[22:23]
	global_load_dword v102, v193, s[20:21]
	global_load_dwordx2 v[104:105], v193, s[20:21] offset:512
	global_load_dwordx3 v[106:108], v193, s[20:21] offset:1024
	global_load_dwordx4 v[110:113], v193, s[20:21] offset:1536
	global_load_dwordx4 v[146:149], v193, s[22:23] offset:16
	global_load_dwordx4 v[114:117], v193, s[20:21] offset:2048
	global_load_dword v118, v193, s[20:21] offset:2064
	global_load_dwordx4 v[120:123], v193, s[20:21] offset:2560
	global_load_dwordx2 v[124:125], v193, s[20:21] offset:2576
	global_load_dwordx4 v[126:129], v193, s[20:21] offset:3072
	global_load_dwordx3 v[130:132], v193, s[20:21] offset:3088
	global_load_dwordx4 v[134:137], v193, s[20:21] offset:3584
	global_load_dwordx4 v[66:69], v193, s[20:21] offset:3600
	v_mov_b32_e32 v1, s0
	ds_read_b64 v[20:21], v1
	ds_read_b64 v[150:151], v1 offset:64
	ds_read_b64 v[152:153], v1 offset:128
	ds_read_b64 v[154:155], v1 offset:192
	ds_read_b64 v[156:157], v1 offset:256
	ds_read_b64 v[158:159], v1 offset:320
	ds_read_b64 v[160:161], v1 offset:384
	ds_read_b64 v[162:163], v1 offset:448
	s_waitcnt lgkmcnt(0)
	v_add_f32_e32 v1, 0, v20
	v_add_f32_e32 v5, 0, v21
	v_add_f32_e32 v1, v1, v150
	v_add_f32_e32 v5, v5, v151
	v_add_f32_e32 v1, v1, v152
	v_add_f32_e32 v5, v5, v153
	v_add_f32_e32 v1, v1, v154
	v_add_f32_e32 v5, v5, v155
	v_add_f32_e32 v1, v1, v156
	v_add_f32_e32 v5, v5, v157
	v_add_f32_e32 v1, v1, v158
	v_add_f32_e32 v5, v5, v159
	v_add_f32_e32 v1, v1, v160
	v_add_f32_e32 v5, v5, v161
	s_mov_b32 s0, 0x7cf8000
	v_add_f32_e32 v1, v1, v162
	v_mul_f32_e32 v7, 0x3b000000, v1
	v_add_f32_e32 v5, v5, v163
	v_mul_f32_e32 v7, v7, v7
	v_fma_f32 v5, v5, s4, -v7
	v_max_f32_e32 v5, 0, v5
	v_add_f32_e32 v5, 0x358637bd, v5
	v_rsq_f32_e32 v5, v5
	v_fmac_f32_e32 v16, 0xbb000000, v1
	v_mul_f32_e32 v1, v16, v5
	v_add_co_u32_e32 v16, vcc, s0, v2
	v_fma_f32 v9, v141, v1, v140
	s_nop 0
	v_addc_co_u32_e32 v17, vcc, 0, v3, vcc
	s_add_i32 s0, 0, 0x22008
	global_store_dword v[16:17], v9, off
	v_mov_b32_e32 v1, s0
	ds_read_b64 v[16:17], v1
	ds_read_b64 v[150:151], v1 offset:64
	ds_read_b64 v[152:153], v1 offset:128
	ds_read_b64 v[154:155], v1 offset:192
	ds_read_b64 v[156:157], v1 offset:256
	ds_read_b64 v[158:159], v1 offset:320
	ds_read_b64 v[160:161], v1 offset:384
	ds_read_b64 v[162:163], v1 offset:448
	s_waitcnt lgkmcnt(0)
	v_add_f32_e32 v1, 0, v16
	v_add_f32_e32 v5, 0, v17
	v_add_f32_e32 v1, v1, v150
	v_add_f32_e32 v5, v5, v151
	v_add_f32_e32 v1, v1, v152
	v_add_f32_e32 v5, v5, v153
	v_add_f32_e32 v1, v1, v154
	v_add_f32_e32 v5, v5, v155
	v_add_f32_e32 v1, v1, v156
	v_add_f32_e32 v5, v5, v157
	v_add_f32_e32 v1, v1, v158
	v_add_f32_e32 v5, v5, v159
	v_add_f32_e32 v1, v1, v160
	v_add_f32_e32 v5, v5, v161
	v_readlane_b32 s0, v251, 17
	v_add_f32_e32 v1, v1, v162
	v_mul_f32_e32 v7, 0x3b000000, v1
	v_add_f32_e32 v5, v5, v163
	v_mul_f32_e32 v7, v7, v7
	v_fma_f32 v5, v5, s4, -v7
	v_max_f32_e32 v5, 0, v5
	v_add_f32_e32 v5, 0x358637bd, v5
	v_rsq_f32_e32 v5, v5
	v_fmac_f32_e32 v14, 0xbb000000, v1
	v_mov_b32_e32 v7, s0
	v_readlane_b32 s0, v251, 18
	v_mul_f32_e32 v1, v14, v5
	v_fma_f32 v11, v141, v1, v140
	global_store_dword v[18:19], v11, off offset:2048
	v_mov_b32_e32 v1, s30
	ds_read_b64 v[14:15], v1
	ds_read_b64 v[150:151], v1 offset:64
	ds_read_b64 v[152:153], v1 offset:128
	ds_read_b64 v[154:155], v1 offset:192
	ds_read_b64 v[156:157], v1 offset:256
	ds_read_b64 v[158:159], v1 offset:320
	ds_read_b64 v[160:161], v1 offset:384
	ds_read_b64 v[162:163], v1 offset:448
	s_waitcnt lgkmcnt(0)
	v_add_f32_e32 v1, 0, v14
	v_add_f32_e32 v5, 0, v15
	v_add_f32_e32 v1, v1, v150
	v_add_f32_e32 v5, v5, v151
	v_add_f32_e32 v1, v1, v152
	v_add_f32_e32 v5, v5, v153
	v_add_f32_e32 v1, v1, v154
	v_add_f32_e32 v5, v5, v155
	v_add_f32_e32 v1, v1, v156
	v_add_f32_e32 v5, v5, v157
	v_add_f32_e32 v1, v1, v158
	v_add_f32_e32 v5, v5, v159
	v_add_f32_e32 v1, v1, v160
	v_add_f32_e32 v5, v5, v161
	s_mov_b32 s0, 0x7cf9000
	v_add_f32_e32 v1, v1, v162
	v_mul_f32_e32 v7, 0x3b000000, v1
	v_add_f32_e32 v5, v5, v163
	v_mul_f32_e32 v7, v7, v7
	v_fma_f32 v5, v5, s4, -v7
	v_max_f32_e32 v5, 0, v5
	v_add_f32_e32 v5, 0x358637bd, v5
	v_rsq_f32_e32 v5, v5
	v_fmac_f32_e32 v12, 0xbb000000, v1
	v_add_co_u32_e32 v14, vcc, s0, v2
	v_mul_f32_e32 v1, v12, v5
	v_fma_f32 v12, v141, v1, v140
	v_addc_co_u32_e32 v15, vcc, 0, v3, vcc
	s_add_i32 s0, 0, 0x22018
	global_store_dword v[14:15], v12, off
	v_mov_b32_e32 v1, s0
	ds_read_b64 v[16:17], v1
	ds_read_b64 v[150:151], v1 offset:64
	ds_read_b64 v[152:153], v1 offset:128
	ds_read_b64 v[154:155], v1 offset:192
	ds_read_b64 v[156:157], v1 offset:256
	ds_read_b64 v[158:159], v1 offset:320
	ds_read_b64 v[160:161], v1 offset:384
	ds_read_b64 v[162:163], v1 offset:448
	s_waitcnt lgkmcnt(0)
	v_add_f32_e32 v1, 0, v16
	v_add_f32_e32 v5, 0, v17
	v_add_f32_e32 v1, v1, v150
	v_add_f32_e32 v5, v5, v151
	v_add_f32_e32 v1, v1, v152
	v_add_f32_e32 v5, v5, v153
	v_add_f32_e32 v1, v1, v154
	v_add_f32_e32 v5, v5, v155
	v_add_f32_e32 v1, v1, v156
	v_add_f32_e32 v5, v5, v157
	v_add_f32_e32 v1, v1, v158
	v_add_f32_e32 v5, v5, v159
	v_add_f32_e32 v1, v1, v160
	v_add_f32_e32 v5, v5, v161
	v_readlane_b32 s0, v251, 24
	v_add_f32_e32 v1, v1, v162
	v_mul_f32_e32 v7, 0x3b000000, v1
	v_add_f32_e32 v5, v5, v163
	v_mul_f32_e32 v7, v7, v7
	v_fma_f32 v5, v5, s4, -v7
	v_max_f32_e32 v5, 0, v5
	v_add_f32_e32 v5, 0x358637bd, v5
	v_rsq_f32_e32 v5, v5
	v_fmac_f32_e32 v10, 0xbb000000, v1
	v_mov_b32_e32 v7, s0
	v_readlane_b32 s0, v251, 25
	v_mul_f32_e32 v1, v10, v5
	v_fma_f32 v10, v141, v1, v140
	global_store_dword v[14:15], v10, off offset:2048
	v_mov_b32_e32 v1, s29
	ds_read_b64 v[14:15], v1
	ds_read_b64 v[150:151], v1 offset:64
	ds_read_b64 v[152:153], v1 offset:128
	ds_read_b64 v[154:155], v1 offset:192
	ds_read_b64 v[156:157], v1 offset:256
	ds_read_b64 v[158:159], v1 offset:320
	ds_read_b64 v[160:161], v1 offset:384
	ds_read_b64 v[162:163], v1 offset:448
	s_waitcnt lgkmcnt(0)
	v_add_f32_e32 v1, 0, v14
	v_add_f32_e32 v5, 0, v15
	v_add_f32_e32 v1, v1, v150
	v_add_f32_e32 v5, v5, v151
	v_add_f32_e32 v1, v1, v152
	v_add_f32_e32 v5, v5, v153
	v_add_f32_e32 v1, v1, v154
	v_add_f32_e32 v5, v5, v155
	v_add_f32_e32 v1, v1, v156
	v_add_f32_e32 v5, v5, v157
	v_add_f32_e32 v1, v1, v158
	v_add_f32_e32 v5, v5, v159
	v_add_f32_e32 v1, v1, v160
	v_add_f32_e32 v5, v5, v161
	s_mov_b32 s0, 0x7cfa000
	v_add_f32_e32 v1, v1, v162
	v_mul_f32_e32 v7, 0x3b000000, v1
	v_add_f32_e32 v5, v5, v163
	v_mul_f32_e32 v7, v7, v7
	v_fma_f32 v5, v5, s4, -v7
	v_max_f32_e32 v5, 0, v5
	v_add_f32_e32 v5, 0x358637bd, v5
	v_rsq_f32_e32 v5, v5
	v_fmac_f32_e32 v8, 0xbb000000, v1
	v_add_co_u32_e32 v14, vcc, s0, v2
	v_mul_f32_e32 v1, v8, v5
	v_fma_f32 v8, v141, v1, v140
	v_addc_co_u32_e32 v15, vcc, 0, v3, vcc
	s_add_i32 s0, 0, 0x22028
	global_store_dword v[14:15], v8, off
	v_mov_b32_e32 v1, s0
	ds_read_b64 v[16:17], v1
	ds_read_b64 v[150:151], v1 offset:64
	ds_read_b64 v[152:153], v1 offset:128
	ds_read_b64 v[154:155], v1 offset:192
	ds_read_b64 v[156:157], v1 offset:256
	ds_read_b64 v[158:159], v1 offset:320
	ds_read_b64 v[160:161], v1 offset:384
	ds_read_b64 v[162:163], v1 offset:448
	s_waitcnt lgkmcnt(0)
	v_add_f32_e32 v1, 0, v16
	v_add_f32_e32 v5, 0, v17
	v_add_f32_e32 v1, v1, v150
	v_add_f32_e32 v5, v5, v151
	v_add_f32_e32 v1, v1, v152
	v_add_f32_e32 v5, v5, v153
	v_add_f32_e32 v1, v1, v154
	v_add_f32_e32 v5, v5, v155
	v_add_f32_e32 v1, v1, v156
	v_add_f32_e32 v5, v5, v157
	v_add_f32_e32 v1, v1, v158
	v_add_f32_e32 v5, v5, v159
	v_add_f32_e32 v1, v1, v160
	v_add_f32_e32 v5, v5, v161
	v_readlane_b32 s0, v251, 31
	v_add_f32_e32 v1, v1, v162
	v_mul_f32_e32 v7, 0x3b000000, v1
	v_add_f32_e32 v5, v5, v163
	v_mul_f32_e32 v7, v7, v7
	v_fma_f32 v5, v5, s4, -v7
	v_max_f32_e32 v5, 0, v5
	v_add_f32_e32 v5, 0x358637bd, v5
	v_rsq_f32_e32 v5, v5
	v_fmac_f32_e32 v6, 0xbb000000, v1
	v_mul_f32_e32 v1, v6, v5
	v_fma_f32 v13, v141, v1, v140
	global_store_dword v[14:15], v13, off offset:2048
	v_mov_b32_e32 v1, s28
	ds_read_b64 v[6:7], v1
	ds_read_b64 v[150:151], v1 offset:64
	ds_read_b64 v[152:153], v1 offset:128
	ds_read_b64 v[154:155], v1 offset:192
	ds_read_b64 v[156:157], v1 offset:256
	ds_read_b64 v[158:159], v1 offset:320
	ds_read_b64 v[160:161], v1 offset:384
	ds_read_b64 v[162:163], v1 offset:448
	s_waitcnt lgkmcnt(0)
	v_add_f32_e32 v1, 0, v6
	v_add_f32_e32 v5, 0, v7
	v_add_f32_e32 v1, v1, v150
	v_add_f32_e32 v5, v5, v151
	v_add_f32_e32 v1, v1, v152
	v_add_f32_e32 v5, v5, v153
	v_add_f32_e32 v1, v1, v154
	v_add_f32_e32 v5, v5, v155
	v_add_f32_e32 v1, v1, v156
	v_add_f32_e32 v5, v5, v157
	v_add_f32_e32 v1, v1, v158
	v_add_f32_e32 v5, v5, v159
	v_add_f32_e32 v1, v1, v160
	v_add_f32_e32 v5, v5, v161
	v_readlane_b32 s16, v250, 5
	v_readlane_b32 s30, v250, 19
	v_readlane_b32 s31, v250, 20
	v_readlane_b32 s17, v250, 6
	v_readlane_b32 s18, v250, 7
	v_readlane_b32 s19, v250, 8
	v_readlane_b32 s20, v250, 9
	v_readlane_b32 s21, v250, 10
	v_readlane_b32 s22, v250, 11
	v_readlane_b32 s23, v250, 12
	v_readlane_b32 s24, v250, 13
	v_readlane_b32 s25, v250, 14
	v_readlane_b32 s26, v250, 15
	v_readlane_b32 s27, v250, 16
	v_readlane_b32 s28, v250, 17
	v_readlane_b32 s29, v250, 18
	s_mov_b32 s0, 0x7cfb000
	v_add_co_u32_e32 v2, vcc, s0, v2
	s_add_i32 s0, 0, 0x22038
	v_add_f32_e32 v1, v1, v162
	v_mul_f32_e32 v6, 0x3b000000, v1
	v_add_f32_e32 v5, v5, v163
	v_mul_f32_e32 v6, v6, v6
	v_fma_f32 v5, v5, s4, -v6
	v_max_f32_e32 v5, 0, v5
	v_add_f32_e32 v5, 0x358637bd, v5
	v_rsq_f32_e32 v5, v5
	v_fmac_f32_e32 v4, 0xbb000000, v1
	v_addc_co_u32_e32 v3, vcc, 0, v3, vcc
	v_mul_f32_e32 v1, v4, v5
	v_fma_f32 v14, v141, v1, v140
	global_store_dword v[2:3], v14, off
	v_mov_b32_e32 v1, s0
	ds_read_b64 v[4:5], v1
	ds_read_b64 v[150:151], v1 offset:64
	ds_read_b64 v[152:153], v1 offset:128
	ds_read_b64 v[154:155], v1 offset:192
	ds_read_b64 v[156:157], v1 offset:256
	ds_read_b64 v[158:159], v1 offset:320
	ds_read_b64 v[160:161], v1 offset:384
	ds_read_b64 v[162:163], v1 offset:448
	s_waitcnt lgkmcnt(0)
	v_add_f32_e32 v1, 0, v4
	v_add_f32_e32 v6, 0, v5
	v_add_f32_e32 v1, v1, v150
	v_add_f32_e32 v6, v6, v151
	v_add_f32_e32 v1, v1, v152
	v_add_f32_e32 v6, v6, v153
	v_add_f32_e32 v1, v1, v154
	v_add_f32_e32 v6, v6, v155
	v_add_f32_e32 v1, v1, v156
	v_add_f32_e32 v6, v6, v157
	v_add_f32_e32 v1, v1, v158
	v_add_f32_e32 v6, v6, v159
	v_add_f32_e32 v1, v1, v160
	v_add_f32_e32 v6, v6, v161
	s_lshl_b64 s[0:1], s[2:3], 7
	v_add_f32_e32 v1, v1, v162
	v_add_f32_e32 v4, v6, v163
	v_mul_f32_e32 v5, 0x3b000000, v1
	v_mul_f32_e32 v5, v5, v5
	v_fma_f32 v4, v4, s4, -v5
	v_max_f32_e32 v4, 0, v4
	v_readlane_b32 s4, v253, 61
	v_add_f32_e32 v4, 0x358637bd, v4
	v_readlane_b32 s5, v253, 62
	s_add_u32 s0, s0, s4
	v_rsq_f32_e32 v4, v4
	s_addc_u32 s1, s1, s5
	s_lshl_b64 s[0:1], s[0:1], 9
	s_add_u32 s0, s30, s0
	v_fmac_f32_e32 v0, 0xbb000000, v1
	s_addc_u32 s1, s31, s1
	s_lshl_b64 s[2:3], s[2:3], 9
	v_readlane_b32 s4, v253, 51
	v_mul_f32_e32 v0, v0, v4
	v_readlane_b32 s5, v253, 52
	s_add_u32 s2, s4, s2
	v_fmac_f32_e32 v140, v141, v0
	s_addc_u32 s3, s5, s3
	s_mov_b64 s[4:5], s[42:43]
	global_store_dword v[2:3], v140, off offset:2048
	s_add_u32 s4, s4, s14
	s_addc_u32 s5, s5, s15
	v_lshl_add_u64 v[4:5], v[64:65], 1, s[4:5]
	s_brev_b32 s2, 40
	v_add_co_u32_e32 v20, vcc, s2, v4
	s_mov_b32 s2, 0x14001000
	s_nop 0
	v_addc_co_u32_e32 v21, vcc, 0, v5, vcc
	s_waitcnt vmcnt(8)
	v_fma_f32 v15, v9, v102, v142
	ds_read2st64_b32 v[6:7], v92 offset0:64 offset1:72
	s_waitcnt lgkmcnt(0)
	v_mul_f32_e32 v6, v6, v15
	v_cvt_pk_bf16_f32 v6, v6, s0
	global_store_short v[20:21], v6, off offset:2048
	v_fma_f32 v6, v9, v104, v143
	v_fmac_f32_e32 v6, v11, v105
	v_mul_f32_e32 v6, v7, v6
	v_cvt_pk_bf16_f32 v15, v6, s0
	v_add_co_u32_e32 v6, vcc, s2, v4
	s_mov_b32 s2, 0x14002000
	s_nop 0
	v_addc_co_u32_e32 v7, vcc, 0, v5, vcc
	global_store_short v[6:7], v15, off offset:2048
	ds_read2st64_b32 v[6:7], v92 offset0:80 offset1:88
	v_add_co_u32_e32 v16, vcc, s2, v4
	s_mov_b32 s2, 0x14003000
	s_nop 0
	v_addc_co_u32_e32 v17, vcc, 0, v5, vcc
	v_fma_f32 v15, v9, v106, v144
	v_fmac_f32_e32 v15, v11, v107
	v_fmac_f32_e32 v15, v12, v108
	s_waitcnt lgkmcnt(0)
	v_mul_f32_e32 v6, v6, v15
	v_cvt_pk_bf16_f32 v6, v6, s0
	global_store_short v[16:17], v6, off offset:2048
	v_fmac_f32_e32 v145, v9, v110
	v_fmac_f32_e32 v145, v11, v111
	v_fmac_f32_e32 v145, v12, v112
	v_fmac_f32_e32 v145, v10, v113
	v_mul_f32_e32 v6, v7, v145
	v_cvt_pk_bf16_f32 v15, v6, s0
	v_add_co_u32_e32 v6, vcc, s2, v4
	s_mov_b32 s2, 0x14004000
	s_nop 0
	v_addc_co_u32_e32 v7, vcc, 0, v5, vcc
	global_store_short v[6:7], v15, off offset:2048
	s_nop 0
	v_fma_f32 v0, v9, v114, v146
	v_fmac_f32_e32 v0, v11, v115
	v_fmac_f32_e32 v0, v12, v116
	v_fmac_f32_e32 v0, v10, v117
	v_fmac_f32_e32 v0, v8, v118
	ds_read2st64_b32 v[6:7], v92 offset0:96 offset1:104
	v_add_co_u32_e32 v16, vcc, s2, v4
	s_mov_b32 s2, 0x14005000
	s_nop 0
	v_addc_co_u32_e32 v17, vcc, 0, v5, vcc
	s_waitcnt lgkmcnt(0)
	v_mul_f32_e32 v0, v6, v0
	v_cvt_pk_bf16_f32 v0, v0, s0
	global_store_short v[16:17], v0, off offset:2048
	s_nop 0
	v_fma_f32 v0, v9, v120, v147
	v_fmac_f32_e32 v0, v11, v121
	v_fmac_f32_e32 v0, v12, v122
	v_fmac_f32_e32 v0, v10, v123
	v_fmac_f32_e32 v0, v8, v124
	v_fmac_f32_e32 v0, v13, v125
	v_mul_f32_e32 v0, v7, v0
	v_cvt_pk_bf16_f32 v6, v0, s0
	v_add_co_u32_e32 v0, vcc, s2, v4
	s_mov_b32 s2, 0x14006000
	s_nop 0
	v_addc_co_u32_e32 v1, vcc, 0, v5, vcc
	global_store_short v[0:1], v6, off offset:2048
	ds_read2st64_b32 v[0:1], v92 offset0:112 offset1:120
	v_add_co_u32_e32 v6, vcc, s2, v4
	v_fma_f32 v2, v9, v126, v148
	v_fmac_f32_e32 v2, v11, v127
	v_fmac_f32_e32 v2, v12, v128
	v_fmac_f32_e32 v2, v10, v129
	v_fmac_f32_e32 v2, v8, v130
	v_fmac_f32_e32 v2, v13, v131
	v_fmac_f32_e32 v2, v14, v132
	s_waitcnt lgkmcnt(0)
	v_mul_f32_e32 v0, v0, v2
	v_cvt_pk_bf16_f32 v0, v0, s0
	v_addc_co_u32_e32 v7, vcc, 0, v5, vcc
	global_store_short v[6:7], v0, off offset:2048
	v_fmac_f32_e32 v149, v9, v134
	v_fmac_f32_e32 v149, v11, v135
	v_fmac_f32_e32 v149, v12, v136
	v_fmac_f32_e32 v149, v10, v137
	v_fmac_f32_e32 v149, v8, v66
	v_fmac_f32_e32 v149, v13, v67
	v_fmac_f32_e32 v149, v14, v68
	v_fmac_f32_e32 v149, v140, v69
	v_mul_f32_e32 v0, v1, v149
	v_cvt_pk_bf16_f32 v2, v0, s0
	v_add_co_u32_e32 v0, vcc, 0x14007000, v4
	s_nop 1
	v_addc_co_u32_e32 v1, vcc, 0, v5, vcc
	global_store_short v[0:1], v2, off offset:2048
	s_waitcnt lgkmcnt(0)
	s_barrier
